# grid barrier: L1 invalidate (acquire) issued at arrival, before the spin, instead of after the flag flips
# speedup vs baseline: 1.0170x; 1.0170x over previous
; __device__ __forceinline__ unsigned xb_ld(unsigned* p) { return __hip_atomic_load(p, __ATOMIC_RELAXED, __HIP_MEMORY_SCOPE_AGENT); }
; __device__ __forceinline__ unsigned xb_add(unsigned* p, unsigned v) { return __hip_atomic_fetch_add(p, v, __ATOMIC_RELAXED, __HIP_MEMORY_SCOPE_AGENT); }
; #define XB_SPIN(cond, bar) do { unsigned _sp = 0; while (cond) { __builtin_amdgcn_s_sleep(0); \
;     if ((++_sp & 255u) == 0u) { if (xb_ld(&(bar)[XB_TMO])) break; if (_sp > XB_SPIN_CAP) { atomicAdd(&(bar)[XB_TMO], 1u); break; } } } } while (0)
; __device__ __forceinline__ void xcd_barrier(XcdBarrier& b, const int tid, const unsigned G) {
;     ...
;     const unsigned nloc = b.nloc, nx = b.nx;
;     const unsigned old = xb_add(&bar[XB_XSUB(b.x)], 1u);
;     const unsigned gen = old / nloc;
;     if (old + 1u == (gen + 1u) * nloc) {
;       __builtin_amdgcn_fence(__ATOMIC_RELEASE, "agent");
;       asm volatile("s_waitcnt vmcnt(0)" ::: "memory");
;       const unsigned og = xb_add(&bar[XB_TOP], 1u);
;       const unsigned tg = og / nx;
;       if (og + 1u == (tg + 1u) * nx) xb_add(&bar[XB_TOPGEN], 1u);
;       else XB_SPIN(xb_ld(&bar[XB_TOPGEN]) == tg, bar);
;       __builtin_amdgcn_fence(__ATOMIC_ACQUIRE, "agent");
;       xb_add(&bar[XB_XGEN(b.x)], 1u);
;       asm volatile("s_waitcnt vmcnt(0)" ::: "memory");
;     } else {
;       XB_SPIN(xb_ld(&bar[XB_XGEN(b.x)]) == gen, bar);
;       __builtin_amdgcn_fence(__ATOMIC_ACQUIRE, "agent");
;       asm volatile("s_waitcnt vmcnt(0)" ::: "memory");
.LBB0_50:
	s_or_b64 exec, exec, s[34:35]
	s_waitcnt vmcnt(0)
	v_readfirstlane_b32 s23, v1
	v_sub_u32_e32 v2, 0, v126
	s_nop 0
	v_add_u32_e32 v1, s23, v0
	v_cvt_f32_u32_e32 v0, v126
	v_rcp_iflag_f32_e32 v0, v0
	s_nop 0
	v_mul_f32_e32 v0, 0x4f7ffffe, v0
	v_cvt_u32_f32_e32 v0, v0
	v_mul_lo_u32 v2, v2, v0
	v_mul_hi_u32 v2, v0, v2
	v_add_u32_e32 v0, v0, v2
	v_mul_hi_u32 v0, v1, v0
	v_mul_lo_u32 v2, v0, v126
	v_sub_u32_e32 v2, v1, v2
	v_cmp_ge_u32_e32 vcc, v2, v126
	v_add_u32_e32 v4, 1, v0
	v_add_u32_e32 v1, 1, v1
	v_cndmask_b32_e32 v0, v0, v4, vcc
	v_sub_u32_e32 v4, v2, v126
	v_cndmask_b32_e32 v2, v2, v4, vcc
	v_cmp_ge_u32_e32 vcc, v2, v126
	v_add_u32_e32 v2, 1, v0
	s_nop 0
	v_cndmask_b32_e32 v0, v0, v2, vcc
	v_mad_u64_u32 v[4:5], s[24:25], v126, v0, v[126:127]
	v_cmp_ne_u32_e32 vcc, v1, v4
	s_and_saveexec_b64 s[24:25], vcc
	s_xor_b64 s[34:35], exec, s[24:25]
	s_cbranch_execz .LBB0_64
	v_readlane_b32 s24, v253, 11
	v_readlane_b32 s25, v253, 12
	s_nop 4
	buffer_inv sc1
	global_load_dword v1, v3, s[24:25] sc1
	s_waitcnt vmcnt(0)
	v_cmp_eq_u32_e32 vcc, v1, v0
	s_and_saveexec_b64 s[36:37], vcc
	s_cbranch_execz .LBB0_63
	s_mov_b32 s23, 1
	s_mov_b64 s[38:39], 0
	s_branch .LBB0_54

; __device__ __forceinline__ unsigned xb_ld(unsigned* p) { return __hip_atomic_load(p, __ATOMIC_RELAXED, __HIP_MEMORY_SCOPE_AGENT); }
; __device__ __forceinline__ unsigned xb_add(unsigned* p, unsigned v) { return __hip_atomic_fetch_add(p, v, __ATOMIC_RELAXED, __HIP_MEMORY_SCOPE_AGENT); }
; #define XB_SPIN(cond, bar) do { unsigned _sp = 0; while (cond) { __builtin_amdgcn_s_sleep(0); \
;     if ((++_sp & 255u) == 0u) { if (xb_ld(&(bar)[XB_TMO])) break; if (_sp > XB_SPIN_CAP) { atomicAdd(&(bar)[XB_TMO], 1u); break; } } } } while (0)
; __device__ __forceinline__ void xcd_barrier(XcdBarrier& b, const int tid, const unsigned G) {
;     ...
;     if (old + 1u == (gen + 1u) * nloc) {
;       __builtin_amdgcn_fence(__ATOMIC_RELEASE, "agent");
;       asm volatile("s_waitcnt vmcnt(0)" ::: "memory");
;       const unsigned og = xb_add(&bar[XB_TOP], 1u);
;       const unsigned tg = og / nx;
;       if (og + 1u == (tg + 1u) * nx) xb_add(&bar[XB_TOPGEN], 1u);
;       else XB_SPIN(xb_ld(&bar[XB_TOPGEN]) == tg, bar);
;       __builtin_amdgcn_fence(__ATOMIC_ACQUIRE, "agent");
;       xb_add(&bar[XB_XGEN(b.x)], 1u);
;       asm volatile("s_waitcnt vmcnt(0)" ::: "memory");
;     } else {
;       XB_SPIN(xb_ld(&bar[XB_XGEN(b.x)]) == gen, bar);
;       __builtin_amdgcn_fence(__ATOMIC_ACQUIRE, "agent");
.LBB0_63:
	s_or_b64 exec, exec, s[36:37]
	s_waitcnt vmcnt(0)
	s_waitcnt vmcnt(0)
.LBB0_64:
	s_andn2_saveexec_b64 s[34:35], s[34:35]
	s_cbranch_execz .LBB0_84
	s_mov_b64 s[36:37], exec
	buffer_wbl2 sc1
	s_waitcnt vmcnt(0)
	buffer_inv sc1
	v_mbcnt_lo_u32_b32 v0, s36, 0
	v_mbcnt_hi_u32_b32 v0, s37, v0
	v_cmp_eq_u32_e32 vcc, 0, v0
	s_and_saveexec_b64 s[38:39], vcc
	s_cbranch_execz .LBB0_67
	s_bcnt1_i32_b64 s23, s[36:37]
	v_readlane_b32 s24, v253, 13
	v_mov_b32_e32 v1, s23
	v_readlane_b32 s25, v253, 14
	s_nop 4
	global_atomic_add v1, v3, v1, s[24:25] sc0

; __device__ __forceinline__ unsigned xb_ld(unsigned* p) { return __hip_atomic_load(p, __ATOMIC_RELAXED, __HIP_MEMORY_SCOPE_AGENT); }
; __device__ __forceinline__ unsigned xb_add(unsigned* p, unsigned v) { return __hip_atomic_fetch_add(p, v, __ATOMIC_RELAXED, __HIP_MEMORY_SCOPE_AGENT); }
; #define XB_SPIN(cond, bar) do { unsigned _sp = 0; while (cond) { __builtin_amdgcn_s_sleep(0); \
;     if ((++_sp & 255u) == 0u) { if (xb_ld(&(bar)[XB_TMO])) break; if (_sp > XB_SPIN_CAP) { atomicAdd(&(bar)[XB_TMO], 1u); break; } } } } while (0)
; __device__ __forceinline__ void xcd_barrier(XcdBarrier& b, const int tid, const unsigned G) {
;     ...
;       const unsigned og = xb_add(&bar[XB_TOP], 1u);
;       const unsigned tg = og / nx;
;       if (og + 1u == (tg + 1u) * nx) xb_add(&bar[XB_TOPGEN], 1u);
;       else XB_SPIN(xb_ld(&bar[XB_TOPGEN]) == tg, bar);
;       __builtin_amdgcn_fence(__ATOMIC_ACQUIRE, "agent");
;       xb_add(&bar[XB_XGEN(b.x)], 1u);
;       asm volatile("s_waitcnt vmcnt(0)" ::: "memory");
.LBB0_81:
	s_or_b64 exec, exec, s[36:37]
	s_mov_b64 s[36:37], exec
	v_mbcnt_lo_u32_b32 v0, s36, 0
	v_mbcnt_hi_u32_b32 v0, s37, v0
	v_cmp_eq_u32_e32 vcc, 0, v0
	s_waitcnt vmcnt(0)
	s_and_saveexec_b64 s[38:39], vcc
	s_cbranch_execz .LBB0_83
	s_bcnt1_i32_b64 s23, s[36:37]
	v_readlane_b32 s24, v253, 11
	v_mov_b32_e32 v0, s23
	v_readlane_b32 s25, v253, 12
	s_nop 4
	global_atomic_add v3, v0, s[24:25]
